# v91 + PREP expert f32->fp8 conversion loop hand-written with contiguous-lane loads (1 KB per load instruction), 4 rows in flight
# baseline (speedup 1.0000x reference)
.LBB1_1147:
.LBB1_1148:
	s_mov_b64 exec, -1
	v_readfirstlane_b32 s5, v6
	s_load_dwordx4 s[72:75], s[0:1], 0xb0
	s_load_dwordx4 s[76:79], s[0:1], 0x100
	s_load_dwordx2 s[80:81], s[0:1], 0x110
	v_lshrrev_b32_e32 v122, 2, v4
	v_mov_b32_e32 v123, 0
	s_waitcnt lgkmcnt(0)
	s_add_u32 s72, s72, s88
	s_addc_u32 s73, s73, s89
	s_add_u32 s74, s74, s88
	s_addc_u32 s75, s75, s89
	s_add_u32 s76, s76, s66
	s_addc_u32 s77, s77, s67
	s_add_u32 s78, s78, s66
	s_addc_u32 s79, s79, s67
.Lgp_loop:
	s_mov_b32 s44, s5
	s_add_u32 s45, s44, s4
	s_add_u32 s46, s45, s4
	s_add_u32 s47, s46, s4
	s_min_u32 s50, s44, 0x7fff
	s_min_u32 s51, s45, 0x7fff
	s_min_u32 s52, s46, 0x7fff
	s_min_u32 s53, s47, 0x7fff
	s_lshr_b32 s6, s50, 14
	s_and_b32 s7, s50, 0x3fff
	s_lshl_b32 s7, s7, 12
	s_cmp_eq_u32 s6, 0
	s_cselect_b32 s8, s72, s74
	s_cselect_b32 s9, s73, s75
	s_add_u32 s8, s8, s7
	s_addc_u32 s9, s9, 0
	global_load_dwordx4 v[16:19], v4, s[8:9] offset:0
	global_load_dwordx4 v[20:23], v4, s[8:9] offset:1024
	global_load_dwordx4 v[24:27], v4, s[8:9] offset:2048
	global_load_dwordx4 v[28:31], v4, s[8:9] offset:3072
	s_lshr_b32 s6, s51, 14
	s_and_b32 s7, s51, 0x3fff
	s_lshl_b32 s7, s7, 12
	s_cmp_eq_u32 s6, 0
	s_cselect_b32 s8, s72, s74
	s_cselect_b32 s9, s73, s75
	s_add_u32 s8, s8, s7
	s_addc_u32 s9, s9, 0
	global_load_dwordx4 v[42:45], v4, s[8:9] offset:0
	global_load_dwordx4 v[46:49], v4, s[8:9] offset:1024
	global_load_dwordx4 v[50:53], v4, s[8:9] offset:2048
	global_load_dwordx4 v[54:57], v4, s[8:9] offset:3072
	s_lshr_b32 s6, s52, 14
	s_and_b32 s7, s52, 0x3fff
	s_lshl_b32 s7, s7, 12
	s_cmp_eq_u32 s6, 0
	s_cselect_b32 s8, s72, s74
	s_cselect_b32 s9, s73, s75
	s_add_u32 s8, s8, s7
	s_addc_u32 s9, s9, 0
	global_load_dwordx4 v[70:73], v4, s[8:9] offset:0
	global_load_dwordx4 v[74:77], v4, s[8:9] offset:1024
	global_load_dwordx4 v[78:81], v4, s[8:9] offset:2048
	global_load_dwordx4 v[82:85], v4, s[8:9] offset:3072
	s_lshr_b32 s6, s53, 14
	s_and_b32 s7, s53, 0x3fff
	s_lshl_b32 s7, s7, 12
	s_cmp_eq_u32 s6, 0
	s_cselect_b32 s8, s72, s74
	s_cselect_b32 s9, s73, s75
	s_add_u32 s8, s8, s7
	s_addc_u32 s9, s9, 0
	global_load_dwordx4 v[86:89], v4, s[8:9] offset:0
	global_load_dwordx4 v[90:93], v4, s[8:9] offset:1024
	global_load_dwordx4 v[94:97], v4, s[8:9] offset:2048
	global_load_dwordx4 v[98:101], v4, s[8:9] offset:3072
	s_waitcnt vmcnt(12)
	v_max3_f32 v102, |v16|, |v17|, |v18|
	v_max3_f32 v103, |v19|, |v20|, |v21|
	v_max3_f32 v104, |v22|, |v23|, |v24|
	v_max3_f32 v105, |v25|, |v26|, |v27|
	v_max3_f32 v106, |v28|, |v29|, |v30|
	v_max3_f32 v102, v102, v103, |v31|
	v_max3_f32 v102, v102, v104, v105
	v_max_f32_e32 v102, v102, v106
	s_nop 1
	v_max_f32_dpp v102, v102, v102 quad_perm:[1,0,3,2] row_mask:0xf bank_mask:0xf
	s_nop 1
	v_max_f32_dpp v102, v102, v102 quad_perm:[2,3,0,1] row_mask:0xf bank_mask:0xf
	s_nop 1
	v_max_f32_dpp v102, v102, v102 row_half_mirror row_mask:0xf bank_mask:0xf
	s_nop 1
	v_max_f32_dpp v102, v102, v102 row_mirror row_mask:0xf bank_mask:0xf
	s_nop 1
	v_readlane_b32 s6, v102, 0
	v_readlane_b32 s7, v102, 16
	v_readlane_b32 s8, v102, 32
	v_readlane_b32 s9, v102, 48
	s_nop 1
	v_mov_b32_e32 v14, s6
	v_max_f32_e32 v14, s7, v14
	v_max_f32_e32 v14, s8, v14
	v_max_f32_e32 v14, s9, v14
	v_mul_f32_e32 v15, 0x3b14f209, v14
	v_cmp_lt_f32_e32 vcc, 0, v14
	s_nop 1
	v_cndmask_b32_e32 v14, 1.0, v15, vcc
	v_div_scale_f32 v15, s[6:7], v14, v14, 1.0
	v_rcp_f32_e32 v103, v15
	v_div_scale_f32 v104, vcc, 1.0, v14, 1.0
	v_fma_f32 v105, -v15, v103, 1.0
	v_fmac_f32_e32 v103, v105, v103
	v_mul_f32_e32 v105, v104, v103
	v_fma_f32 v106, -v15, v105, v104
	v_fmac_f32_e32 v105, v106, v103
	v_fma_f32 v15, -v15, v105, v104
	s_nop 1
	v_div_fmas_f32 v15, v15, v103, v105
	v_div_fixup_f32 v15, v15, v14, 1.0
	v_mul_f32_e32 v16, v16, v15
	v_mul_f32_e32 v17, v17, v15
	v_mul_f32_e32 v18, v18, v15
	v_mul_f32_e32 v19, v19, v15
	v_mul_f32_e32 v20, v20, v15
	v_mul_f32_e32 v21, v21, v15
	v_mul_f32_e32 v22, v22, v15
	v_mul_f32_e32 v23, v23, v15
	v_mul_f32_e32 v24, v24, v15
	v_mul_f32_e32 v25, v25, v15
	v_mul_f32_e32 v26, v26, v15
	v_mul_f32_e32 v27, v27, v15
	v_mul_f32_e32 v28, v28, v15
	v_mul_f32_e32 v29, v29, v15
	v_mul_f32_e32 v30, v30, v15
	v_mul_f32_e32 v31, v31, v15
	v_mov_b32_e32 v118, 0
	v_mov_b32_e32 v119, 0
	v_mov_b32_e32 v120, 0
	v_mov_b32_e32 v121, 0
	v_cvt_pk_fp8_f32 v118, v16, v17
	v_cvt_pk_fp8_f32 v119, v20, v21
	v_cvt_pk_fp8_f32 v120, v24, v25
	v_cvt_pk_fp8_f32 v121, v28, v29
	s_nop 0
	v_cvt_pk_fp8_f32 v118, v18, v19 op_sel:[0,0,1]
	v_cvt_pk_fp8_f32 v119, v22, v23 op_sel:[0,0,1]
	v_cvt_pk_fp8_f32 v120, v26, v27 op_sel:[0,0,1]
	v_cvt_pk_fp8_f32 v121, v30, v31 op_sel:[0,0,1]
	s_cmp_lt_u32 s44, 0x8000
	s_cbranch_scc0 .Lgp_skip0
	s_lshr_b32 s6, s44, 14
	s_and_b32 s7, s44, 0x3fff
	s_lshl_b32 s10, s7, 10
	s_cmp_eq_u32 s6, 0
	s_cselect_b32 s8, s76, s78
	s_cselect_b32 s9, s77, s79
	s_add_u32 s8, s8, s10
	s_addc_u32 s9, s9, 0
	global_store_dword v122, v118, s[8:9] offset:0
	global_store_dword v122, v119, s[8:9] offset:256
	global_store_dword v122, v120, s[8:9] offset:512
	global_store_dword v122, v121, s[8:9] offset:768
	s_lshl_b32 s6, s6, 14
	s_add_u32 s6, s6, s7
	s_add_u32 s6, s6, s90
	s_lshl_b32 s6, s6, 2
	s_add_u32 s8, s80, s6
	s_addc_u32 s9, s81, 0
	s_mov_b64 exec, 1
	global_store_dword v123, v14, s[8:9]
	s_mov_b64 exec, -1
.Lgp_skip0:
	s_waitcnt vmcnt(8)
	v_max3_f32 v102, |v42|, |v43|, |v44|
	v_max3_f32 v103, |v45|, |v46|, |v47|
	v_max3_f32 v104, |v48|, |v49|, |v50|
	v_max3_f32 v105, |v51|, |v52|, |v53|
	v_max3_f32 v106, |v54|, |v55|, |v56|
	v_max3_f32 v102, v102, v103, |v57|
	v_max3_f32 v102, v102, v104, v105
	v_max_f32_e32 v102, v102, v106
	s_nop 1
	v_max_f32_dpp v102, v102, v102 quad_perm:[1,0,3,2] row_mask:0xf bank_mask:0xf
	s_nop 1
	v_max_f32_dpp v102, v102, v102 quad_perm:[2,3,0,1] row_mask:0xf bank_mask:0xf
	s_nop 1
	v_max_f32_dpp v102, v102, v102 row_half_mirror row_mask:0xf bank_mask:0xf
	s_nop 1
	v_max_f32_dpp v102, v102, v102 row_mirror row_mask:0xf bank_mask:0xf
	s_nop 1
	v_readlane_b32 s6, v102, 0
	v_readlane_b32 s7, v102, 16
	v_readlane_b32 s8, v102, 32
	v_readlane_b32 s9, v102, 48
	s_nop 1
	v_mov_b32_e32 v14, s6
	v_max_f32_e32 v14, s7, v14
	v_max_f32_e32 v14, s8, v14
	v_max_f32_e32 v14, s9, v14
	v_mul_f32_e32 v15, 0x3b14f209, v14
	v_cmp_lt_f32_e32 vcc, 0, v14
	s_nop 1
	v_cndmask_b32_e32 v14, 1.0, v15, vcc
	v_div_scale_f32 v15, s[6:7], v14, v14, 1.0
	v_rcp_f32_e32 v103, v15
	v_div_scale_f32 v104, vcc, 1.0, v14, 1.0
	v_fma_f32 v105, -v15, v103, 1.0
	v_fmac_f32_e32 v103, v105, v103
	v_mul_f32_e32 v105, v104, v103
	v_fma_f32 v106, -v15, v105, v104
	v_fmac_f32_e32 v105, v106, v103
	v_fma_f32 v15, -v15, v105, v104
	s_nop 1
	v_div_fmas_f32 v15, v15, v103, v105
	v_div_fixup_f32 v15, v15, v14, 1.0
	v_mul_f32_e32 v42, v42, v15
	v_mul_f32_e32 v43, v43, v15
	v_mul_f32_e32 v44, v44, v15
	v_mul_f32_e32 v45, v45, v15
	v_mul_f32_e32 v46, v46, v15
	v_mul_f32_e32 v47, v47, v15
	v_mul_f32_e32 v48, v48, v15
	v_mul_f32_e32 v49, v49, v15
	v_mul_f32_e32 v50, v50, v15
	v_mul_f32_e32 v51, v51, v15
	v_mul_f32_e32 v52, v52, v15
	v_mul_f32_e32 v53, v53, v15
	v_mul_f32_e32 v54, v54, v15
	v_mul_f32_e32 v55, v55, v15
	v_mul_f32_e32 v56, v56, v15
	v_mul_f32_e32 v57, v57, v15
	v_mov_b32_e32 v118, 0
	v_mov_b32_e32 v119, 0
	v_mov_b32_e32 v120, 0
	v_mov_b32_e32 v121, 0
	v_cvt_pk_fp8_f32 v118, v42, v43
	v_cvt_pk_fp8_f32 v119, v46, v47
	v_cvt_pk_fp8_f32 v120, v50, v51
	v_cvt_pk_fp8_f32 v121, v54, v55
	s_nop 0
	v_cvt_pk_fp8_f32 v118, v44, v45 op_sel:[0,0,1]
	v_cvt_pk_fp8_f32 v119, v48, v49 op_sel:[0,0,1]
	v_cvt_pk_fp8_f32 v120, v52, v53 op_sel:[0,0,1]
	v_cvt_pk_fp8_f32 v121, v56, v57 op_sel:[0,0,1]
	s_cmp_lt_u32 s45, 0x8000
	s_cbranch_scc0 .Lgp_skip1
	s_lshr_b32 s6, s45, 14
	s_and_b32 s7, s45, 0x3fff
	s_lshl_b32 s10, s7, 10
	s_cmp_eq_u32 s6, 0
	s_cselect_b32 s8, s76, s78
	s_cselect_b32 s9, s77, s79
	s_add_u32 s8, s8, s10
	s_addc_u32 s9, s9, 0
	global_store_dword v122, v118, s[8:9] offset:0
	global_store_dword v122, v119, s[8:9] offset:256
	global_store_dword v122, v120, s[8:9] offset:512
	global_store_dword v122, v121, s[8:9] offset:768
	s_lshl_b32 s6, s6, 14
	s_add_u32 s6, s6, s7
	s_add_u32 s6, s6, s90
	s_lshl_b32 s6, s6, 2
	s_add_u32 s8, s80, s6
	s_addc_u32 s9, s81, 0
	s_mov_b64 exec, 1
	global_store_dword v123, v14, s[8:9]
	s_mov_b64 exec, -1
.Lgp_skip1:
	s_waitcnt vmcnt(4)
	v_max3_f32 v102, |v70|, |v71|, |v72|
	v_max3_f32 v103, |v73|, |v74|, |v75|
	v_max3_f32 v104, |v76|, |v77|, |v78|
	v_max3_f32 v105, |v79|, |v80|, |v81|
	v_max3_f32 v106, |v82|, |v83|, |v84|
	v_max3_f32 v102, v102, v103, |v85|
	v_max3_f32 v102, v102, v104, v105
	v_max_f32_e32 v102, v102, v106
	s_nop 1
	v_max_f32_dpp v102, v102, v102 quad_perm:[1,0,3,2] row_mask:0xf bank_mask:0xf
	s_nop 1
	v_max_f32_dpp v102, v102, v102 quad_perm:[2,3,0,1] row_mask:0xf bank_mask:0xf
	s_nop 1
	v_max_f32_dpp v102, v102, v102 row_half_mirror row_mask:0xf bank_mask:0xf
	s_nop 1
	v_max_f32_dpp v102, v102, v102 row_mirror row_mask:0xf bank_mask:0xf
	s_nop 1
	v_readlane_b32 s6, v102, 0
	v_readlane_b32 s7, v102, 16
	v_readlane_b32 s8, v102, 32
	v_readlane_b32 s9, v102, 48
	s_nop 1
	v_mov_b32_e32 v14, s6
	v_max_f32_e32 v14, s7, v14
	v_max_f32_e32 v14, s8, v14
	v_max_f32_e32 v14, s9, v14
	v_mul_f32_e32 v15, 0x3b14f209, v14
	v_cmp_lt_f32_e32 vcc, 0, v14
	s_nop 1
	v_cndmask_b32_e32 v14, 1.0, v15, vcc
	v_div_scale_f32 v15, s[6:7], v14, v14, 1.0
	v_rcp_f32_e32 v103, v15
	v_div_scale_f32 v104, vcc, 1.0, v14, 1.0
	v_fma_f32 v105, -v15, v103, 1.0
	v_fmac_f32_e32 v103, v105, v103
	v_mul_f32_e32 v105, v104, v103
	v_fma_f32 v106, -v15, v105, v104
	v_fmac_f32_e32 v105, v106, v103
	v_fma_f32 v15, -v15, v105, v104
	s_nop 1
	v_div_fmas_f32 v15, v15, v103, v105
	v_div_fixup_f32 v15, v15, v14, 1.0
	v_mul_f32_e32 v70, v70, v15
	v_mul_f32_e32 v71, v71, v15
	v_mul_f32_e32 v72, v72, v15
	v_mul_f32_e32 v73, v73, v15
	v_mul_f32_e32 v74, v74, v15
	v_mul_f32_e32 v75, v75, v15
	v_mul_f32_e32 v76, v76, v15
	v_mul_f32_e32 v77, v77, v15
	v_mul_f32_e32 v78, v78, v15
	v_mul_f32_e32 v79, v79, v15
	v_mul_f32_e32 v80, v80, v15
	v_mul_f32_e32 v81, v81, v15
	v_mul_f32_e32 v82, v82, v15
	v_mul_f32_e32 v83, v83, v15
	v_mul_f32_e32 v84, v84, v15
	v_mul_f32_e32 v85, v85, v15
	v_mov_b32_e32 v118, 0
	v_mov_b32_e32 v119, 0
	v_mov_b32_e32 v120, 0
	v_mov_b32_e32 v121, 0
	v_cvt_pk_fp8_f32 v118, v70, v71
	v_cvt_pk_fp8_f32 v119, v74, v75
	v_cvt_pk_fp8_f32 v120, v78, v79
	v_cvt_pk_fp8_f32 v121, v82, v83
	s_nop 0
	v_cvt_pk_fp8_f32 v118, v72, v73 op_sel:[0,0,1]
	v_cvt_pk_fp8_f32 v119, v76, v77 op_sel:[0,0,1]
	v_cvt_pk_fp8_f32 v120, v80, v81 op_sel:[0,0,1]
	v_cvt_pk_fp8_f32 v121, v84, v85 op_sel:[0,0,1]
	s_cmp_lt_u32 s46, 0x8000
	s_cbranch_scc0 .Lgp_skip2
	s_lshr_b32 s6, s46, 14
	s_and_b32 s7, s46, 0x3fff
	s_lshl_b32 s10, s7, 10
	s_cmp_eq_u32 s6, 0
	s_cselect_b32 s8, s76, s78
	s_cselect_b32 s9, s77, s79
	s_add_u32 s8, s8, s10
	s_addc_u32 s9, s9, 0
	global_store_dword v122, v118, s[8:9] offset:0
	global_store_dword v122, v119, s[8:9] offset:256
	global_store_dword v122, v120, s[8:9] offset:512
	global_store_dword v122, v121, s[8:9] offset:768
	s_lshl_b32 s6, s6, 14
	s_add_u32 s6, s6, s7
	s_add_u32 s6, s6, s90
	s_lshl_b32 s6, s6, 2
	s_add_u32 s8, s80, s6
	s_addc_u32 s9, s81, 0
	s_mov_b64 exec, 1
	global_store_dword v123, v14, s[8:9]
	s_mov_b64 exec, -1
.Lgp_skip2:
	s_waitcnt vmcnt(0)
	v_max3_f32 v102, |v86|, |v87|, |v88|
	v_max3_f32 v103, |v89|, |v90|, |v91|
	v_max3_f32 v104, |v92|, |v93|, |v94|
	v_max3_f32 v105, |v95|, |v96|, |v97|
	v_max3_f32 v106, |v98|, |v99|, |v100|
	v_max3_f32 v102, v102, v103, |v101|
	v_max3_f32 v102, v102, v104, v105
	v_max_f32_e32 v102, v102, v106
	s_nop 1
	v_max_f32_dpp v102, v102, v102 quad_perm:[1,0,3,2] row_mask:0xf bank_mask:0xf
	s_nop 1
	v_max_f32_dpp v102, v102, v102 quad_perm:[2,3,0,1] row_mask:0xf bank_mask:0xf
	s_nop 1
	v_max_f32_dpp v102, v102, v102 row_half_mirror row_mask:0xf bank_mask:0xf
	s_nop 1
	v_max_f32_dpp v102, v102, v102 row_mirror row_mask:0xf bank_mask:0xf
	s_nop 1
	v_readlane_b32 s6, v102, 0
	v_readlane_b32 s7, v102, 16
	v_readlane_b32 s8, v102, 32
	v_readlane_b32 s9, v102, 48
	s_nop 1
	v_mov_b32_e32 v14, s6
	v_max_f32_e32 v14, s7, v14
	v_max_f32_e32 v14, s8, v14
	v_max_f32_e32 v14, s9, v14
	v_mul_f32_e32 v15, 0x3b14f209, v14
	v_cmp_lt_f32_e32 vcc, 0, v14
	s_nop 1
	v_cndmask_b32_e32 v14, 1.0, v15, vcc
	v_div_scale_f32 v15, s[6:7], v14, v14, 1.0
	v_rcp_f32_e32 v103, v15
	v_div_scale_f32 v104, vcc, 1.0, v14, 1.0
	v_fma_f32 v105, -v15, v103, 1.0
	v_fmac_f32_e32 v103, v105, v103
	v_mul_f32_e32 v105, v104, v103
	v_fma_f32 v106, -v15, v105, v104
	v_fmac_f32_e32 v105, v106, v103
	v_fma_f32 v15, -v15, v105, v104
	s_nop 1
	v_div_fmas_f32 v15, v15, v103, v105
	v_div_fixup_f32 v15, v15, v14, 1.0
	v_mul_f32_e32 v86, v86, v15
	v_mul_f32_e32 v87, v87, v15
	v_mul_f32_e32 v88, v88, v15
	v_mul_f32_e32 v89, v89, v15
	v_mul_f32_e32 v90, v90, v15
	v_mul_f32_e32 v91, v91, v15
	v_mul_f32_e32 v92, v92, v15
	v_mul_f32_e32 v93, v93, v15
	v_mul_f32_e32 v94, v94, v15
	v_mul_f32_e32 v95, v95, v15
	v_mul_f32_e32 v96, v96, v15
	v_mul_f32_e32 v97, v97, v15
	v_mul_f32_e32 v98, v98, v15
	v_mul_f32_e32 v99, v99, v15
	v_mul_f32_e32 v100, v100, v15
	v_mul_f32_e32 v101, v101, v15
	v_mov_b32_e32 v118, 0
	v_mov_b32_e32 v119, 0
	v_mov_b32_e32 v120, 0
	v_mov_b32_e32 v121, 0
	v_cvt_pk_fp8_f32 v118, v86, v87
	v_cvt_pk_fp8_f32 v119, v90, v91
	v_cvt_pk_fp8_f32 v120, v94, v95
	v_cvt_pk_fp8_f32 v121, v98, v99
	s_nop 0
	v_cvt_pk_fp8_f32 v118, v88, v89 op_sel:[0,0,1]
	v_cvt_pk_fp8_f32 v119, v92, v93 op_sel:[0,0,1]
	v_cvt_pk_fp8_f32 v120, v96, v97 op_sel:[0,0,1]
	v_cvt_pk_fp8_f32 v121, v100, v101 op_sel:[0,0,1]
	s_cmp_lt_u32 s47, 0x8000
	s_cbranch_scc0 .Lgp_skip3
	s_lshr_b32 s6, s47, 14
	s_and_b32 s7, s47, 0x3fff
	s_lshl_b32 s10, s7, 10
	s_cmp_eq_u32 s6, 0
	s_cselect_b32 s8, s76, s78
	s_cselect_b32 s9, s77, s79
	s_add_u32 s8, s8, s10
	s_addc_u32 s9, s9, 0
	global_store_dword v122, v118, s[8:9] offset:0
	global_store_dword v122, v119, s[8:9] offset:256
	global_store_dword v122, v120, s[8:9] offset:512
	global_store_dword v122, v121, s[8:9] offset:768
	s_lshl_b32 s6, s6, 14
	s_add_u32 s6, s6, s7
	s_add_u32 s6, s6, s90
	s_lshl_b32 s6, s6, 2
	s_add_u32 s8, s80, s6
	s_addc_u32 s9, s81, 0
	s_mov_b64 exec, 1
	global_store_dword v123, v14, s[8:9]
	s_mov_b64 exec, -1
.Lgp_skip3:
	s_add_u32 s5, s47, s4
	s_cmp_lt_u32 s5, 0x8000
	s_cbranch_scc1 .Lgp_loop
	s_waitcnt vmcnt(0)
